# P0 rows loop rewritten: gains preloaded once, 4 rows of loads in flight per wave, counted vmcnt
# speedup vs baseline: 1.0067x; 1.0067x over previous
.LBB0_31:
	s_cmpk_gt_i32 s12, 0x407f
	s_cbranch_scc1 .LBB0_34
	s_waitcnt lgkmcnt(0)
	v_lshlrev_b32_e32 v1, 4, v2
	global_load_dwordx4 v[40:43], v1, s[16:17]
	global_load_dwordx4 v[44:47], v1, s[16:17] offset:1024
	global_load_dwordx4 v[48:51], v1, s[16:17] offset:2048
	global_load_dwordx4 v[52:55], v1, s[16:17] offset:3072
	v_mov_b32_e32 v3, 0x358637bd
	s_mov_b32 s25, 0xf800000
	v_mov_b32_e32 v6, 0x260
	s_movk_i32 s26, 0x7fff
	s_mov_b32 s27, 0xffff0000
	s_add_u32 s20, s14, 0x1b00000
	s_addc_u32 s21, s15, 0
	s_add_u32 s22, s14, 0x26900000
	s_addc_u32 s23, s15, 0
	s_mov_b32 s40, s12
.Lp0_batch:
	s_mov_b32 s60, s40
	s_mov_b32 s38, s60
	s_add_i32 s39, s38, 0xffffc000
	s_cmpk_lt_i32 s38, 0x4000
	s_cselect_b32 s39, s38, s39
	s_cselect_b32 s44, s8, s10
	s_cselect_b32 s45, s9, s11
	s_cselect_b32 s46, s4, s6
	s_cselect_b32 s47, s5, s7
	s_lshl_b32 s38, s39, 12
	s_add_u32 s44, s44, s38
	s_addc_u32 s45, s45, 0
	s_lshl_b32 s38, s39, 10
	s_add_u32 s46, s46, s38
	s_addc_u32 s47, s47, 0
	global_load_dwordx4 v[64:67], v1, s[44:45] nt
	global_load_dwordx4 v[68:71], v1, s[44:45] offset:1024 nt
	global_load_dwordx4 v[72:75], v1, s[44:45] offset:2048 nt
	global_load_dwordx4 v[76:79], v1, s[44:45] offset:3072 nt
	global_load_dwordx4 v[80:83], v1, s[46:47] nt
	s_add_i32 s61, s60, s34
	s_cmpk_lt_i32 s61, 0x4080
	s_cselect_b32 s38, s61, s40
	s_add_i32 s39, s38, 0xffffc000
	s_cmpk_lt_i32 s38, 0x4000
	s_cselect_b32 s39, s38, s39
	s_cselect_b32 s48, s8, s10
	s_cselect_b32 s49, s9, s11
	s_cselect_b32 s50, s4, s6
	s_cselect_b32 s51, s5, s7
	s_lshl_b32 s38, s39, 12
	s_add_u32 s48, s48, s38
	s_addc_u32 s49, s49, 0
	s_lshl_b32 s38, s39, 10
	s_add_u32 s50, s50, s38
	s_addc_u32 s51, s51, 0
	global_load_dwordx4 v[84:87], v1, s[48:49] nt
	global_load_dwordx4 v[88:91], v1, s[48:49] offset:1024 nt
	global_load_dwordx4 v[92:95], v1, s[48:49] offset:2048 nt
	global_load_dwordx4 v[96:99], v1, s[48:49] offset:3072 nt
	global_load_dwordx4 v[100:103], v1, s[50:51] nt
	s_add_i32 s62, s61, s34
	s_cmpk_lt_i32 s62, 0x4080
	s_cselect_b32 s38, s62, s40
	s_add_i32 s39, s38, 0xffffc000
	s_cmpk_lt_i32 s38, 0x4000
	s_cselect_b32 s39, s38, s39
	s_cselect_b32 s52, s8, s10
	s_cselect_b32 s53, s9, s11
	s_cselect_b32 s54, s4, s6
	s_cselect_b32 s55, s5, s7
	s_lshl_b32 s38, s39, 12
	s_add_u32 s52, s52, s38
	s_addc_u32 s53, s53, 0
	s_lshl_b32 s38, s39, 10
	s_add_u32 s54, s54, s38
	s_addc_u32 s55, s55, 0
	global_load_dwordx4 v[104:107], v1, s[52:53] nt
	global_load_dwordx4 v[108:111], v1, s[52:53] offset:1024 nt
	global_load_dwordx4 v[112:115], v1, s[52:53] offset:2048 nt
	global_load_dwordx4 v[116:119], v1, s[52:53] offset:3072 nt
	global_load_dwordx4 v[120:123], v1, s[54:55] nt
	s_add_i32 s63, s62, s34
	s_cmpk_lt_i32 s63, 0x4080
	s_cselect_b32 s38, s63, s40
	s_add_i32 s39, s38, 0xffffc000
	s_cmpk_lt_i32 s38, 0x4000
	s_cselect_b32 s39, s38, s39
	s_cselect_b32 s56, s8, s10
	s_cselect_b32 s57, s9, s11
	s_cselect_b32 s58, s4, s6
	s_cselect_b32 s59, s5, s7
	s_lshl_b32 s38, s39, 12
	s_add_u32 s56, s56, s38
	s_addc_u32 s57, s57, 0
	s_lshl_b32 s38, s39, 10
	s_add_u32 s58, s58, s38
	s_addc_u32 s59, s59, 0
	global_load_dwordx4 v[124:127], v1, s[56:57] nt
	global_load_dwordx4 v[128:131], v1, s[56:57] offset:1024 nt
	global_load_dwordx4 v[132:135], v1, s[56:57] offset:2048 nt
	global_load_dwordx4 v[136:139], v1, s[56:57] offset:3072 nt
	global_load_dwordx4 v[140:143], v1, s[58:59] nt
	s_lshl_b32 s38, s60, 11
	s_add_u32 s30, s20, s38
	s_addc_u32 s31, s21, 0
	s_lshl_b32 s38, s60, 9
	s_add_u32 s36, s22, s38
	s_addc_u32 s37, s23, 0
	s_waitcnt vmcnt(15)
	v_mul_f32_e32 v7, v65, v65
	v_mul_f32_e32 v30, v67, v67
	v_mul_f32_e32 v31, v69, v69
	v_mul_f32_e32 v32, v71, v71
	v_mul_f32_e32 v33, v73, v73
	v_mul_f32_e32 v34, v75, v75
	v_fmac_f32_e32 v7, v64, v64
	v_fmac_f32_e32 v30, v66, v66
	v_fmac_f32_e32 v31, v68, v68
	v_fmac_f32_e32 v32, v70, v70
	v_mul_f32_e32 v35, v77, v77
	v_mul_f32_e32 v36, v79, v79
	v_fmac_f32_e32 v33, v72, v72
	v_fmac_f32_e32 v34, v74, v74
	v_add_f32_e32 v7, v7, v30
	v_add_f32_e32 v30, v31, v32
	v_fmac_f32_e32 v35, v76, v76
	v_fmac_f32_e32 v36, v78, v78
	v_add_f32_e32 v31, v33, v34
	v_add_f32_e32 v7, v7, v30
	v_add_f32_e32 v32, v35, v36
	v_add_f32_e32 v7, v7, v31
	v_add_f32_e32 v7, v7, v32
	s_nop 1
	v_add_f32_dpp v7, v7, v7 quad_perm:[1,0,3,2] row_mask:0xf bank_mask:0xf bound_ctrl:1
	s_nop 1
	v_add_f32_dpp v7, v7, v7 quad_perm:[2,3,0,1] row_mask:0xf bank_mask:0xf bound_ctrl:1
	s_nop 1
	v_add_f32_dpp v7, v7, v7 row_half_mirror row_mask:0xf bank_mask:0xf bound_ctrl:1
	s_nop 1
	v_add_f32_dpp v7, v7, v7 row_ror:8 row_mask:0xf bank_mask:0xf bound_ctrl:1
	v_mov_b32_e32 v30, v7
	s_nop 1
	v_permlane16_swap_b32_e32 v7, v30
	v_add_f32_e32 v7, v7, v30
	v_mov_b32_e32 v30, v7
	s_nop 1
	v_permlane32_swap_b32_e32 v7, v30
	v_add_f32_e32 v7, v7, v30
	v_fmamk_f32 v7, v7, 0x3a800000, v3
	v_mul_f32_e32 v30, 0x4f800000, v7
	v_cmp_gt_f32_e32 vcc, s25, v7
	s_nop 1
	v_cndmask_b32_e32 v7, v7, v30, vcc
	v_sqrt_f32_e32 v30, v7
	s_nop 0
	v_add_u32_e32 v31, -1, v30
	v_add_u32_e32 v32, 1, v30
	v_fma_f32 v33, -v31, v30, v7
	v_fma_f32 v34, -v32, v30, v7
	v_cmp_ge_f32_e64 s[28:29], 0, v33
	s_nop 1
	v_cndmask_b32_e64 v30, v30, v31, s[28:29]
	v_cmp_lt_f32_e64 s[28:29], 0, v34
	s_nop 1
	v_cndmask_b32_e64 v30, v30, v32, s[28:29]
	v_mul_f32_e32 v31, 0x37800000, v30
	v_cndmask_b32_e32 v30, v30, v31, vcc
	v_cmp_class_f32_e32 vcc, v7, v6
	s_nop 1
	v_cndmask_b32_e32 v7, v30, v7, vcc
	v_div_scale_f32 v30, s[28:29], v7, v7, 1.0
	v_rcp_f32_e32 v32, v30
	v_div_scale_f32 v31, vcc, 1.0, v7, 1.0
	v_fma_f32 v33, -v30, v32, 1.0
	v_fmac_f32_e32 v32, v33, v32
	v_mul_f32_e32 v33, v31, v32
	v_fma_f32 v34, -v30, v33, v31
	v_fmac_f32_e32 v33, v34, v32
	v_fma_f32 v30, -v30, v33, v31
	v_div_fmas_f32 v30, v30, v32, v33
	v_div_fixup_f32 v7, v30, v7, 1.0
	v_mul_f32_e32 v12, v64, v7
	v_mul_f32_e32 v14, v66, v7
	v_mul_f32_e32 v13, v65, v7
	v_mul_f32_e32 v15, v67, v7
	v_mul_f32_e32 v8, v40, v12
	v_mul_f32_e32 v10, v42, v14
	v_mul_f32_e32 v9, v41, v13
	v_mul_f32_e32 v11, v43, v15
	v_bfe_u32 v12, v8, 16, 1
	v_bfe_u32 v14, v10, 16, 1
	v_bfe_u32 v13, v9, 16, 1
	v_bfe_u32 v15, v11, 16, 1
	v_add3_u32 v8, v8, v12, s26
	v_add3_u32 v10, v10, v14, s26
	v_add3_u32 v9, v9, v13, s26
	v_add3_u32 v11, v11, v15, s26
	v_lshrrev_b32_e32 v8, 16, v8
	v_lshrrev_b32_e32 v10, 16, v10
	v_and_or_b32 v20, v9, s27, v8
	v_and_or_b32 v21, v11, s27, v10
	global_store_dwordx2 v0, v[20:21], s[30:31]
	v_mul_f32_e32 v12, v68, v7
	v_mul_f32_e32 v14, v70, v7
	v_mul_f32_e32 v13, v69, v7
	v_mul_f32_e32 v15, v71, v7
	v_mul_f32_e32 v8, v44, v12
	v_mul_f32_e32 v10, v46, v14
	v_mul_f32_e32 v9, v45, v13
	v_mul_f32_e32 v11, v47, v15
	v_bfe_u32 v12, v8, 16, 1
	v_bfe_u32 v14, v10, 16, 1
	v_bfe_u32 v13, v9, 16, 1
	v_bfe_u32 v15, v11, 16, 1
	v_add3_u32 v8, v8, v12, s26
	v_add3_u32 v10, v10, v14, s26
	v_add3_u32 v9, v9, v13, s26
	v_add3_u32 v11, v11, v15, s26
	v_lshrrev_b32_e32 v8, 16, v8
	v_lshrrev_b32_e32 v10, 16, v10
	v_and_or_b32 v22, v9, s27, v8
	v_and_or_b32 v23, v11, s27, v10
	global_store_dwordx2 v0, v[22:23], s[30:31] offset:512
	v_mul_f32_e32 v12, v72, v7
	v_mul_f32_e32 v14, v74, v7
	v_mul_f32_e32 v13, v73, v7
	v_mul_f32_e32 v15, v75, v7
	v_mul_f32_e32 v8, v48, v12
	v_mul_f32_e32 v10, v50, v14
	v_mul_f32_e32 v9, v49, v13
	v_mul_f32_e32 v11, v51, v15
	v_bfe_u32 v12, v8, 16, 1
	v_bfe_u32 v14, v10, 16, 1
	v_bfe_u32 v13, v9, 16, 1
	v_bfe_u32 v15, v11, 16, 1
	v_add3_u32 v8, v8, v12, s26
	v_add3_u32 v10, v10, v14, s26
	v_add3_u32 v9, v9, v13, s26
	v_add3_u32 v11, v11, v15, s26
	v_lshrrev_b32_e32 v8, 16, v8
	v_lshrrev_b32_e32 v10, 16, v10
	v_and_or_b32 v24, v9, s27, v8
	v_and_or_b32 v25, v11, s27, v10
	global_store_dwordx2 v0, v[24:25], s[30:31] offset:1024
	v_mul_f32_e32 v12, v76, v7
	v_mul_f32_e32 v14, v78, v7
	v_mul_f32_e32 v13, v77, v7
	v_mul_f32_e32 v15, v79, v7
	v_mul_f32_e32 v8, v52, v12
	v_mul_f32_e32 v10, v54, v14
	v_mul_f32_e32 v9, v53, v13
	v_mul_f32_e32 v11, v55, v15
	v_bfe_u32 v12, v8, 16, 1
	v_bfe_u32 v14, v10, 16, 1
	v_bfe_u32 v13, v9, 16, 1
	v_bfe_u32 v15, v11, 16, 1
	v_add3_u32 v8, v8, v12, s26
	v_add3_u32 v10, v10, v14, s26
	v_add3_u32 v9, v9, v13, s26
	v_add3_u32 v11, v11, v15, s26
	v_lshrrev_b32_e32 v8, 16, v8
	v_lshrrev_b32_e32 v10, 16, v10
	v_and_or_b32 v26, v9, s27, v8
	v_and_or_b32 v27, v11, s27, v10
	global_store_dwordx2 v0, v[26:27], s[30:31] offset:1536
	v_bfe_u32 v8, v80, 16, 1
	v_bfe_u32 v9, v81, 16, 1
	v_bfe_u32 v10, v82, 16, 1
	v_bfe_u32 v11, v83, 16, 1
	v_add3_u32 v8, v80, v8, s26
	v_add3_u32 v9, v81, v9, s26
	v_add3_u32 v10, v82, v10, s26
	v_add3_u32 v11, v83, v11, s26
	v_lshrrev_b32_e32 v8, 16, v8
	v_lshrrev_b32_e32 v10, 16, v10
	v_and_or_b32 v28, v9, s27, v8
	v_and_or_b32 v29, v11, s27, v10
	global_store_dwordx2 v0, v[28:29], s[36:37]
	s_cmpk_gt_i32 s61, 0x407f
	s_cbranch_scc1 .Lp0_done
	s_lshl_b32 s38, s61, 11
	s_add_u32 s30, s20, s38
	s_addc_u32 s31, s21, 0
	s_lshl_b32 s38, s61, 9
	s_add_u32 s36, s22, s38
	s_addc_u32 s37, s23, 0
	s_waitcnt vmcnt(15)
	v_mul_f32_e32 v7, v85, v85
	v_mul_f32_e32 v30, v87, v87
	v_mul_f32_e32 v31, v89, v89
	v_mul_f32_e32 v32, v91, v91
	v_mul_f32_e32 v33, v93, v93
	v_mul_f32_e32 v34, v95, v95
	v_fmac_f32_e32 v7, v84, v84
	v_fmac_f32_e32 v30, v86, v86
	v_fmac_f32_e32 v31, v88, v88
	v_fmac_f32_e32 v32, v90, v90
	v_mul_f32_e32 v35, v97, v97
	v_mul_f32_e32 v36, v99, v99
	v_fmac_f32_e32 v33, v92, v92
	v_fmac_f32_e32 v34, v94, v94
	v_add_f32_e32 v7, v7, v30
	v_add_f32_e32 v30, v31, v32
	v_fmac_f32_e32 v35, v96, v96
	v_fmac_f32_e32 v36, v98, v98
	v_add_f32_e32 v31, v33, v34
	v_add_f32_e32 v7, v7, v30
	v_add_f32_e32 v32, v35, v36
	v_add_f32_e32 v7, v7, v31
	v_add_f32_e32 v7, v7, v32
	s_nop 1
	v_add_f32_dpp v7, v7, v7 quad_perm:[1,0,3,2] row_mask:0xf bank_mask:0xf bound_ctrl:1
	s_nop 1
	v_add_f32_dpp v7, v7, v7 quad_perm:[2,3,0,1] row_mask:0xf bank_mask:0xf bound_ctrl:1
	s_nop 1
	v_add_f32_dpp v7, v7, v7 row_half_mirror row_mask:0xf bank_mask:0xf bound_ctrl:1
	s_nop 1
	v_add_f32_dpp v7, v7, v7 row_ror:8 row_mask:0xf bank_mask:0xf bound_ctrl:1
	v_mov_b32_e32 v30, v7
	s_nop 1
	v_permlane16_swap_b32_e32 v7, v30
	v_add_f32_e32 v7, v7, v30
	v_mov_b32_e32 v30, v7
	s_nop 1
	v_permlane32_swap_b32_e32 v7, v30
	v_add_f32_e32 v7, v7, v30
	v_fmamk_f32 v7, v7, 0x3a800000, v3
	v_mul_f32_e32 v30, 0x4f800000, v7
	v_cmp_gt_f32_e32 vcc, s25, v7
	s_nop 1
	v_cndmask_b32_e32 v7, v7, v30, vcc
	v_sqrt_f32_e32 v30, v7
	s_nop 0
	v_add_u32_e32 v31, -1, v30
	v_add_u32_e32 v32, 1, v30
	v_fma_f32 v33, -v31, v30, v7
	v_fma_f32 v34, -v32, v30, v7
	v_cmp_ge_f32_e64 s[28:29], 0, v33
	s_nop 1
	v_cndmask_b32_e64 v30, v30, v31, s[28:29]
	v_cmp_lt_f32_e64 s[28:29], 0, v34
	s_nop 1
	v_cndmask_b32_e64 v30, v30, v32, s[28:29]
	v_mul_f32_e32 v31, 0x37800000, v30
	v_cndmask_b32_e32 v30, v30, v31, vcc
	v_cmp_class_f32_e32 vcc, v7, v6
	s_nop 1
	v_cndmask_b32_e32 v7, v30, v7, vcc
	v_div_scale_f32 v30, s[28:29], v7, v7, 1.0
	v_rcp_f32_e32 v32, v30
	v_div_scale_f32 v31, vcc, 1.0, v7, 1.0
	v_fma_f32 v33, -v30, v32, 1.0
	v_fmac_f32_e32 v32, v33, v32
	v_mul_f32_e32 v33, v31, v32
	v_fma_f32 v34, -v30, v33, v31
	v_fmac_f32_e32 v33, v34, v32
	v_fma_f32 v30, -v30, v33, v31
	v_div_fmas_f32 v30, v30, v32, v33
	v_div_fixup_f32 v7, v30, v7, 1.0
	v_mul_f32_e32 v12, v84, v7
	v_mul_f32_e32 v14, v86, v7
	v_mul_f32_e32 v13, v85, v7
	v_mul_f32_e32 v15, v87, v7
	v_mul_f32_e32 v8, v40, v12
	v_mul_f32_e32 v10, v42, v14
	v_mul_f32_e32 v9, v41, v13
	v_mul_f32_e32 v11, v43, v15
	v_bfe_u32 v12, v8, 16, 1
	v_bfe_u32 v14, v10, 16, 1
	v_bfe_u32 v13, v9, 16, 1
	v_bfe_u32 v15, v11, 16, 1
	v_add3_u32 v8, v8, v12, s26
	v_add3_u32 v10, v10, v14, s26
	v_add3_u32 v9, v9, v13, s26
	v_add3_u32 v11, v11, v15, s26
	v_lshrrev_b32_e32 v8, 16, v8
	v_lshrrev_b32_e32 v10, 16, v10
	v_and_or_b32 v20, v9, s27, v8
	v_and_or_b32 v21, v11, s27, v10
	global_store_dwordx2 v0, v[20:21], s[30:31]
	v_mul_f32_e32 v12, v88, v7
	v_mul_f32_e32 v14, v90, v7
	v_mul_f32_e32 v13, v89, v7
	v_mul_f32_e32 v15, v91, v7
	v_mul_f32_e32 v8, v44, v12
	v_mul_f32_e32 v10, v46, v14
	v_mul_f32_e32 v9, v45, v13
	v_mul_f32_e32 v11, v47, v15
	v_bfe_u32 v12, v8, 16, 1
	v_bfe_u32 v14, v10, 16, 1
	v_bfe_u32 v13, v9, 16, 1
	v_bfe_u32 v15, v11, 16, 1
	v_add3_u32 v8, v8, v12, s26
	v_add3_u32 v10, v10, v14, s26
	v_add3_u32 v9, v9, v13, s26
	v_add3_u32 v11, v11, v15, s26
	v_lshrrev_b32_e32 v8, 16, v8
	v_lshrrev_b32_e32 v10, 16, v10
	v_and_or_b32 v22, v9, s27, v8
	v_and_or_b32 v23, v11, s27, v10
	global_store_dwordx2 v0, v[22:23], s[30:31] offset:512
	v_mul_f32_e32 v12, v92, v7
	v_mul_f32_e32 v14, v94, v7
	v_mul_f32_e32 v13, v93, v7
	v_mul_f32_e32 v15, v95, v7
	v_mul_f32_e32 v8, v48, v12
	v_mul_f32_e32 v10, v50, v14
	v_mul_f32_e32 v9, v49, v13
	v_mul_f32_e32 v11, v51, v15
	v_bfe_u32 v12, v8, 16, 1
	v_bfe_u32 v14, v10, 16, 1
	v_bfe_u32 v13, v9, 16, 1
	v_bfe_u32 v15, v11, 16, 1
	v_add3_u32 v8, v8, v12, s26
	v_add3_u32 v10, v10, v14, s26
	v_add3_u32 v9, v9, v13, s26
	v_add3_u32 v11, v11, v15, s26
	v_lshrrev_b32_e32 v8, 16, v8
	v_lshrrev_b32_e32 v10, 16, v10
	v_and_or_b32 v24, v9, s27, v8
	v_and_or_b32 v25, v11, s27, v10
	global_store_dwordx2 v0, v[24:25], s[30:31] offset:1024
	v_mul_f32_e32 v12, v96, v7
	v_mul_f32_e32 v14, v98, v7
	v_mul_f32_e32 v13, v97, v7
	v_mul_f32_e32 v15, v99, v7
	v_mul_f32_e32 v8, v52, v12
	v_mul_f32_e32 v10, v54, v14
	v_mul_f32_e32 v9, v53, v13
	v_mul_f32_e32 v11, v55, v15
	v_bfe_u32 v12, v8, 16, 1
	v_bfe_u32 v14, v10, 16, 1
	v_bfe_u32 v13, v9, 16, 1
	v_bfe_u32 v15, v11, 16, 1
	v_add3_u32 v8, v8, v12, s26
	v_add3_u32 v10, v10, v14, s26
	v_add3_u32 v9, v9, v13, s26
	v_add3_u32 v11, v11, v15, s26
	v_lshrrev_b32_e32 v8, 16, v8
	v_lshrrev_b32_e32 v10, 16, v10
	v_and_or_b32 v26, v9, s27, v8
	v_and_or_b32 v27, v11, s27, v10
	global_store_dwordx2 v0, v[26:27], s[30:31] offset:1536
	v_bfe_u32 v8, v100, 16, 1
	v_bfe_u32 v9, v101, 16, 1
	v_bfe_u32 v10, v102, 16, 1
	v_bfe_u32 v11, v103, 16, 1
	v_add3_u32 v8, v100, v8, s26
	v_add3_u32 v9, v101, v9, s26
	v_add3_u32 v10, v102, v10, s26
	v_add3_u32 v11, v103, v11, s26
	v_lshrrev_b32_e32 v8, 16, v8
	v_lshrrev_b32_e32 v10, 16, v10
	v_and_or_b32 v28, v9, s27, v8
	v_and_or_b32 v29, v11, s27, v10
	global_store_dwordx2 v0, v[28:29], s[36:37]
	s_cmpk_gt_i32 s62, 0x407f
	s_cbranch_scc1 .Lp0_done
	s_lshl_b32 s38, s62, 11
	s_add_u32 s30, s20, s38
	s_addc_u32 s31, s21, 0
	s_lshl_b32 s38, s62, 9
	s_add_u32 s36, s22, s38
	s_addc_u32 s37, s23, 0
	s_waitcnt vmcnt(15)
	v_mul_f32_e32 v7, v105, v105
	v_mul_f32_e32 v30, v107, v107
	v_mul_f32_e32 v31, v109, v109
	v_mul_f32_e32 v32, v111, v111
	v_mul_f32_e32 v33, v113, v113
	v_mul_f32_e32 v34, v115, v115
	v_fmac_f32_e32 v7, v104, v104
	v_fmac_f32_e32 v30, v106, v106
	v_fmac_f32_e32 v31, v108, v108
	v_fmac_f32_e32 v32, v110, v110
	v_mul_f32_e32 v35, v117, v117
	v_mul_f32_e32 v36, v119, v119
	v_fmac_f32_e32 v33, v112, v112
	v_fmac_f32_e32 v34, v114, v114
	v_add_f32_e32 v7, v7, v30
	v_add_f32_e32 v30, v31, v32
	v_fmac_f32_e32 v35, v116, v116
	v_fmac_f32_e32 v36, v118, v118
	v_add_f32_e32 v31, v33, v34
	v_add_f32_e32 v7, v7, v30
	v_add_f32_e32 v32, v35, v36
	v_add_f32_e32 v7, v7, v31
	v_add_f32_e32 v7, v7, v32
	s_nop 1
	v_add_f32_dpp v7, v7, v7 quad_perm:[1,0,3,2] row_mask:0xf bank_mask:0xf bound_ctrl:1
	s_nop 1
	v_add_f32_dpp v7, v7, v7 quad_perm:[2,3,0,1] row_mask:0xf bank_mask:0xf bound_ctrl:1
	s_nop 1
	v_add_f32_dpp v7, v7, v7 row_half_mirror row_mask:0xf bank_mask:0xf bound_ctrl:1
	s_nop 1
	v_add_f32_dpp v7, v7, v7 row_ror:8 row_mask:0xf bank_mask:0xf bound_ctrl:1
	v_mov_b32_e32 v30, v7
	s_nop 1
	v_permlane16_swap_b32_e32 v7, v30
	v_add_f32_e32 v7, v7, v30
	v_mov_b32_e32 v30, v7
	s_nop 1
	v_permlane32_swap_b32_e32 v7, v30
	v_add_f32_e32 v7, v7, v30
	v_fmamk_f32 v7, v7, 0x3a800000, v3
	v_mul_f32_e32 v30, 0x4f800000, v7
	v_cmp_gt_f32_e32 vcc, s25, v7
	s_nop 1
	v_cndmask_b32_e32 v7, v7, v30, vcc
	v_sqrt_f32_e32 v30, v7
	s_nop 0
	v_add_u32_e32 v31, -1, v30
	v_add_u32_e32 v32, 1, v30
	v_fma_f32 v33, -v31, v30, v7
	v_fma_f32 v34, -v32, v30, v7
	v_cmp_ge_f32_e64 s[28:29], 0, v33
	s_nop 1
	v_cndmask_b32_e64 v30, v30, v31, s[28:29]
	v_cmp_lt_f32_e64 s[28:29], 0, v34
	s_nop 1
	v_cndmask_b32_e64 v30, v30, v32, s[28:29]
	v_mul_f32_e32 v31, 0x37800000, v30
	v_cndmask_b32_e32 v30, v30, v31, vcc
	v_cmp_class_f32_e32 vcc, v7, v6
	s_nop 1
	v_cndmask_b32_e32 v7, v30, v7, vcc
	v_div_scale_f32 v30, s[28:29], v7, v7, 1.0
	v_rcp_f32_e32 v32, v30
	v_div_scale_f32 v31, vcc, 1.0, v7, 1.0
	v_fma_f32 v33, -v30, v32, 1.0
	v_fmac_f32_e32 v32, v33, v32
	v_mul_f32_e32 v33, v31, v32
	v_fma_f32 v34, -v30, v33, v31
	v_fmac_f32_e32 v33, v34, v32
	v_fma_f32 v30, -v30, v33, v31
	v_div_fmas_f32 v30, v30, v32, v33
	v_div_fixup_f32 v7, v30, v7, 1.0
	v_mul_f32_e32 v12, v104, v7
	v_mul_f32_e32 v14, v106, v7
	v_mul_f32_e32 v13, v105, v7
	v_mul_f32_e32 v15, v107, v7
	v_mul_f32_e32 v8, v40, v12
	v_mul_f32_e32 v10, v42, v14
	v_mul_f32_e32 v9, v41, v13
	v_mul_f32_e32 v11, v43, v15
	v_bfe_u32 v12, v8, 16, 1
	v_bfe_u32 v14, v10, 16, 1
	v_bfe_u32 v13, v9, 16, 1
	v_bfe_u32 v15, v11, 16, 1
	v_add3_u32 v8, v8, v12, s26
	v_add3_u32 v10, v10, v14, s26
	v_add3_u32 v9, v9, v13, s26
	v_add3_u32 v11, v11, v15, s26
	v_lshrrev_b32_e32 v8, 16, v8
	v_lshrrev_b32_e32 v10, 16, v10
	v_and_or_b32 v20, v9, s27, v8
	v_and_or_b32 v21, v11, s27, v10
	global_store_dwordx2 v0, v[20:21], s[30:31]
	v_mul_f32_e32 v12, v108, v7
	v_mul_f32_e32 v14, v110, v7
	v_mul_f32_e32 v13, v109, v7
	v_mul_f32_e32 v15, v111, v7
	v_mul_f32_e32 v8, v44, v12
	v_mul_f32_e32 v10, v46, v14
	v_mul_f32_e32 v9, v45, v13
	v_mul_f32_e32 v11, v47, v15
	v_bfe_u32 v12, v8, 16, 1
	v_bfe_u32 v14, v10, 16, 1
	v_bfe_u32 v13, v9, 16, 1
	v_bfe_u32 v15, v11, 16, 1
	v_add3_u32 v8, v8, v12, s26
	v_add3_u32 v10, v10, v14, s26
	v_add3_u32 v9, v9, v13, s26
	v_add3_u32 v11, v11, v15, s26
	v_lshrrev_b32_e32 v8, 16, v8
	v_lshrrev_b32_e32 v10, 16, v10
	v_and_or_b32 v22, v9, s27, v8
	v_and_or_b32 v23, v11, s27, v10
	global_store_dwordx2 v0, v[22:23], s[30:31] offset:512
	v_mul_f32_e32 v12, v112, v7
	v_mul_f32_e32 v14, v114, v7
	v_mul_f32_e32 v13, v113, v7
	v_mul_f32_e32 v15, v115, v7
	v_mul_f32_e32 v8, v48, v12
	v_mul_f32_e32 v10, v50, v14
	v_mul_f32_e32 v9, v49, v13
	v_mul_f32_e32 v11, v51, v15
	v_bfe_u32 v12, v8, 16, 1
	v_bfe_u32 v14, v10, 16, 1
	v_bfe_u32 v13, v9, 16, 1
	v_bfe_u32 v15, v11, 16, 1
	v_add3_u32 v8, v8, v12, s26
	v_add3_u32 v10, v10, v14, s26
	v_add3_u32 v9, v9, v13, s26
	v_add3_u32 v11, v11, v15, s26
	v_lshrrev_b32_e32 v8, 16, v8
	v_lshrrev_b32_e32 v10, 16, v10
	v_and_or_b32 v24, v9, s27, v8
	v_and_or_b32 v25, v11, s27, v10
	global_store_dwordx2 v0, v[24:25], s[30:31] offset:1024
	v_mul_f32_e32 v12, v116, v7
	v_mul_f32_e32 v14, v118, v7
	v_mul_f32_e32 v13, v117, v7
	v_mul_f32_e32 v15, v119, v7
	v_mul_f32_e32 v8, v52, v12
	v_mul_f32_e32 v10, v54, v14
	v_mul_f32_e32 v9, v53, v13
	v_mul_f32_e32 v11, v55, v15
	v_bfe_u32 v12, v8, 16, 1
	v_bfe_u32 v14, v10, 16, 1
	v_bfe_u32 v13, v9, 16, 1
	v_bfe_u32 v15, v11, 16, 1
	v_add3_u32 v8, v8, v12, s26
	v_add3_u32 v10, v10, v14, s26
	v_add3_u32 v9, v9, v13, s26
	v_add3_u32 v11, v11, v15, s26
	v_lshrrev_b32_e32 v8, 16, v8
	v_lshrrev_b32_e32 v10, 16, v10
	v_and_or_b32 v26, v9, s27, v8
	v_and_or_b32 v27, v11, s27, v10
	global_store_dwordx2 v0, v[26:27], s[30:31] offset:1536
	v_bfe_u32 v8, v120, 16, 1
	v_bfe_u32 v9, v121, 16, 1
	v_bfe_u32 v10, v122, 16, 1
	v_bfe_u32 v11, v123, 16, 1
	v_add3_u32 v8, v120, v8, s26
	v_add3_u32 v9, v121, v9, s26
	v_add3_u32 v10, v122, v10, s26
	v_add3_u32 v11, v123, v11, s26
	v_lshrrev_b32_e32 v8, 16, v8
	v_lshrrev_b32_e32 v10, 16, v10
	v_and_or_b32 v28, v9, s27, v8
	v_and_or_b32 v29, v11, s27, v10
	global_store_dwordx2 v0, v[28:29], s[36:37]
	s_cmpk_gt_i32 s63, 0x407f
	s_cbranch_scc1 .Lp0_done
	s_lshl_b32 s38, s63, 11
	s_add_u32 s30, s20, s38
	s_addc_u32 s31, s21, 0
	s_lshl_b32 s38, s63, 9
	s_add_u32 s36, s22, s38
	s_addc_u32 s37, s23, 0
	s_waitcnt vmcnt(15)
	v_mul_f32_e32 v7, v125, v125
	v_mul_f32_e32 v30, v127, v127
	v_mul_f32_e32 v31, v129, v129
	v_mul_f32_e32 v32, v131, v131
	v_mul_f32_e32 v33, v133, v133
	v_mul_f32_e32 v34, v135, v135
	v_fmac_f32_e32 v7, v124, v124
	v_fmac_f32_e32 v30, v126, v126
	v_fmac_f32_e32 v31, v128, v128
	v_fmac_f32_e32 v32, v130, v130
	v_mul_f32_e32 v35, v137, v137
	v_mul_f32_e32 v36, v139, v139
	v_fmac_f32_e32 v33, v132, v132
	v_fmac_f32_e32 v34, v134, v134
	v_add_f32_e32 v7, v7, v30
	v_add_f32_e32 v30, v31, v32
	v_fmac_f32_e32 v35, v136, v136
	v_fmac_f32_e32 v36, v138, v138
	v_add_f32_e32 v31, v33, v34
	v_add_f32_e32 v7, v7, v30
	v_add_f32_e32 v32, v35, v36
	v_add_f32_e32 v7, v7, v31
	v_add_f32_e32 v7, v7, v32
	s_nop 1
	v_add_f32_dpp v7, v7, v7 quad_perm:[1,0,3,2] row_mask:0xf bank_mask:0xf bound_ctrl:1
	s_nop 1
	v_add_f32_dpp v7, v7, v7 quad_perm:[2,3,0,1] row_mask:0xf bank_mask:0xf bound_ctrl:1
	s_nop 1
	v_add_f32_dpp v7, v7, v7 row_half_mirror row_mask:0xf bank_mask:0xf bound_ctrl:1
	s_nop 1
	v_add_f32_dpp v7, v7, v7 row_ror:8 row_mask:0xf bank_mask:0xf bound_ctrl:1
	v_mov_b32_e32 v30, v7
	s_nop 1
	v_permlane16_swap_b32_e32 v7, v30
	v_add_f32_e32 v7, v7, v30
	v_mov_b32_e32 v30, v7
	s_nop 1
	v_permlane32_swap_b32_e32 v7, v30
	v_add_f32_e32 v7, v7, v30
	v_fmamk_f32 v7, v7, 0x3a800000, v3
	v_mul_f32_e32 v30, 0x4f800000, v7
	v_cmp_gt_f32_e32 vcc, s25, v7
	s_nop 1
	v_cndmask_b32_e32 v7, v7, v30, vcc
	v_sqrt_f32_e32 v30, v7
	s_nop 0
	v_add_u32_e32 v31, -1, v30
	v_add_u32_e32 v32, 1, v30
	v_fma_f32 v33, -v31, v30, v7
	v_fma_f32 v34, -v32, v30, v7
	v_cmp_ge_f32_e64 s[28:29], 0, v33
	s_nop 1
	v_cndmask_b32_e64 v30, v30, v31, s[28:29]
	v_cmp_lt_f32_e64 s[28:29], 0, v34
	s_nop 1
	v_cndmask_b32_e64 v30, v30, v32, s[28:29]
	v_mul_f32_e32 v31, 0x37800000, v30
	v_cndmask_b32_e32 v30, v30, v31, vcc
	v_cmp_class_f32_e32 vcc, v7, v6
	s_nop 1
	v_cndmask_b32_e32 v7, v30, v7, vcc
	v_div_scale_f32 v30, s[28:29], v7, v7, 1.0
	v_rcp_f32_e32 v32, v30
	v_div_scale_f32 v31, vcc, 1.0, v7, 1.0
	v_fma_f32 v33, -v30, v32, 1.0
	v_fmac_f32_e32 v32, v33, v32
	v_mul_f32_e32 v33, v31, v32
	v_fma_f32 v34, -v30, v33, v31
	v_fmac_f32_e32 v33, v34, v32
	v_fma_f32 v30, -v30, v33, v31
	v_div_fmas_f32 v30, v30, v32, v33
	v_div_fixup_f32 v7, v30, v7, 1.0
	v_mul_f32_e32 v12, v124, v7
	v_mul_f32_e32 v14, v126, v7
	v_mul_f32_e32 v13, v125, v7
	v_mul_f32_e32 v15, v127, v7
	v_mul_f32_e32 v8, v40, v12
	v_mul_f32_e32 v10, v42, v14
	v_mul_f32_e32 v9, v41, v13
	v_mul_f32_e32 v11, v43, v15
	v_bfe_u32 v12, v8, 16, 1
	v_bfe_u32 v14, v10, 16, 1
	v_bfe_u32 v13, v9, 16, 1
	v_bfe_u32 v15, v11, 16, 1
	v_add3_u32 v8, v8, v12, s26
	v_add3_u32 v10, v10, v14, s26
	v_add3_u32 v9, v9, v13, s26
	v_add3_u32 v11, v11, v15, s26
	v_lshrrev_b32_e32 v8, 16, v8
	v_lshrrev_b32_e32 v10, 16, v10
	v_and_or_b32 v20, v9, s27, v8
	v_and_or_b32 v21, v11, s27, v10
	global_store_dwordx2 v0, v[20:21], s[30:31]
	v_mul_f32_e32 v12, v128, v7
	v_mul_f32_e32 v14, v130, v7
	v_mul_f32_e32 v13, v129, v7
	v_mul_f32_e32 v15, v131, v7
	v_mul_f32_e32 v8, v44, v12
	v_mul_f32_e32 v10, v46, v14
	v_mul_f32_e32 v9, v45, v13
	v_mul_f32_e32 v11, v47, v15
	v_bfe_u32 v12, v8, 16, 1
	v_bfe_u32 v14, v10, 16, 1
	v_bfe_u32 v13, v9, 16, 1
	v_bfe_u32 v15, v11, 16, 1
	v_add3_u32 v8, v8, v12, s26
	v_add3_u32 v10, v10, v14, s26
	v_add3_u32 v9, v9, v13, s26
	v_add3_u32 v11, v11, v15, s26
	v_lshrrev_b32_e32 v8, 16, v8
	v_lshrrev_b32_e32 v10, 16, v10
	v_and_or_b32 v22, v9, s27, v8
	v_and_or_b32 v23, v11, s27, v10
	global_store_dwordx2 v0, v[22:23], s[30:31] offset:512
	v_mul_f32_e32 v12, v132, v7
	v_mul_f32_e32 v14, v134, v7
	v_mul_f32_e32 v13, v133, v7
	v_mul_f32_e32 v15, v135, v7
	v_mul_f32_e32 v8, v48, v12
	v_mul_f32_e32 v10, v50, v14
	v_mul_f32_e32 v9, v49, v13
	v_mul_f32_e32 v11, v51, v15
	v_bfe_u32 v12, v8, 16, 1
	v_bfe_u32 v14, v10, 16, 1
	v_bfe_u32 v13, v9, 16, 1
	v_bfe_u32 v15, v11, 16, 1
	v_add3_u32 v8, v8, v12, s26
	v_add3_u32 v10, v10, v14, s26
	v_add3_u32 v9, v9, v13, s26
	v_add3_u32 v11, v11, v15, s26
	v_lshrrev_b32_e32 v8, 16, v8
	v_lshrrev_b32_e32 v10, 16, v10
	v_and_or_b32 v24, v9, s27, v8
	v_and_or_b32 v25, v11, s27, v10
	global_store_dwordx2 v0, v[24:25], s[30:31] offset:1024
	v_mul_f32_e32 v12, v136, v7
	v_mul_f32_e32 v14, v138, v7
	v_mul_f32_e32 v13, v137, v7
	v_mul_f32_e32 v15, v139, v7
	v_mul_f32_e32 v8, v52, v12
	v_mul_f32_e32 v10, v54, v14
	v_mul_f32_e32 v9, v53, v13
	v_mul_f32_e32 v11, v55, v15
	v_bfe_u32 v12, v8, 16, 1
	v_bfe_u32 v14, v10, 16, 1
	v_bfe_u32 v13, v9, 16, 1
	v_bfe_u32 v15, v11, 16, 1
	v_add3_u32 v8, v8, v12, s26
	v_add3_u32 v10, v10, v14, s26
	v_add3_u32 v9, v9, v13, s26
	v_add3_u32 v11, v11, v15, s26
	v_lshrrev_b32_e32 v8, 16, v8
	v_lshrrev_b32_e32 v10, 16, v10
	v_and_or_b32 v26, v9, s27, v8
	v_and_or_b32 v27, v11, s27, v10
	global_store_dwordx2 v0, v[26:27], s[30:31] offset:1536
	v_bfe_u32 v8, v140, 16, 1
	v_bfe_u32 v9, v141, 16, 1
	v_bfe_u32 v10, v142, 16, 1
	v_bfe_u32 v11, v143, 16, 1
	v_add3_u32 v8, v140, v8, s26
	v_add3_u32 v9, v141, v9, s26
	v_add3_u32 v10, v142, v10, s26
	v_add3_u32 v11, v143, v11, s26
	v_lshrrev_b32_e32 v8, 16, v8
	v_lshrrev_b32_e32 v10, 16, v10
	v_and_or_b32 v28, v9, s27, v8
	v_and_or_b32 v29, v11, s27, v10
	global_store_dwordx2 v0, v[28:29], s[36:37]
	s_lshl_b32 s38, s34, 2
	s_add_i32 s40, s40, s38
	s_cmpk_gt_i32 s40, 0x407f
	s_cbranch_scc0 .Lp0_batch
.Lp0_done:
	s_waitcnt vmcnt(0)
	v_mov_b32_e32 v1, 0
